# v30 + end-of-compute-segment s_barrier issued 4 MFMAs early (prio 2 trailing) in the three generic GEMM loops
# baseline (speedup 1.0000x reference)
; #define PG8_STAGE(bufoff, gbase, voff) do { _Pragma("unroll") for (int _i = 0; _i < 2; ++_i) \
;         __builtin_amdgcn_global_load_lds((const unsigned*)((const char*)(gbase) + (voff)[_i]), (LAS unsigned*)(lds + (bufoff) + ldsw + _i * 8192), 16, 0, 0); } while (0)
; #define PG8_LDA(dst, b, h) do { _Pragma("unroll") for (int m = 0; m < 4; ++m) _Pragma("unroll") for (int k = 0; k < 2; ++k) dst[m][k] = *(const LAS bf16x8*)(lds + PG8_SA(b, h) + aoff + m * 2048 + k * 1024); } while (0)
; #define PG8_LDB(dst, b, h) do { _Pragma("unroll") for (int n = 0; n < 2; ++n) _Pragma("unroll") for (int k = 0; k < 2; ++k) dst[n][k] = *(const LAS bf16x8*)(lds + PG8_SB(b, h) + boff + n * 2048 + k * 1024); } while (0)
; #define PG8_MMA(ai, bj, At, Bt) do { __builtin_amdgcn_s_setprio(1); _Pragma("unroll") for (int m = 0; m < 4; ++m) _Pragma("unroll") for (int n = 0; n < 2; ++n) _Pragma("unroll") for (int k = 0; k < 2; ++k) \
;         acc[ai][bj][m][n] = __builtin_amdgcn_mfma_f32_16x16x32_bf16(Bt[n][k], At[m][k], acc[ai][bj][m][n], 0, 0, 0); __builtin_amdgcn_s_setprio(0); } while (0)
; #define PG8_WAIT_V(n) asm volatile("s_waitcnt vmcnt(" #n ")" ::: "memory")
; #define PG8_WAIT_L(n) asm volatile("s_waitcnt lgkmcnt(" #n ")" ::: "memory")
; #define PG8_BAR __builtin_amdgcn_s_barrier()
; #define PG8_SCHED __builtin_amdgcn_sched_barrier(0)
; template <class Epi, class Sched>
; __device__ __forceinline__ void gemm_phase(LAS unsigned char* lds, const Gemm g, Sched S, const Epi& E) {
;     ...
;         for (int t = 0; t < nt; t += 2) {
;             const bool last = (t == nt - 2);
;             const char* a1 = cA + (size_t)(t + 1) * kstep;
;             const char* a2 = last ? nA : cA + (size_t)(t + 2) * kstep; const char* b2 = last ? nB : cB + (size_t)(t + 2) * kstep;
;             const char* a3 = a2 + kstep; const char* b3 = b2 + kstep;
;             PG8_LDB(B0, 0, 0); PG8_LDB(B1, 0, 1); PG8_SCHED; PG8_LDA(At, 0, 0); PG8_STAGE(PG8_SA(1, 1), a1 + hstepA, voffA);
;             PG8_WAIT_V(8); PG8_WAIT_L(0); PG8_BAR; PG8_MMA(0, 0, At, B0); PG8_MMA(0, 1, At, B1); PG8_BAR; PG8_SCHED;
;             PG8_LDA(At, 0, 1); PG8_STAGE(PG8_SB(0, 0), b2, voffB); PG8_STAGE(PG8_SB(0, 1), b2 + hstepB, voffB); PG8_STAGE(PG8_SA(0, 0), a2, voffA);
;             PG8_WAIT_V(8); PG8_WAIT_L(0); PG8_BAR; PG8_MMA(1, 0, At, B0); PG8_MMA(1, 1, At, B1); PG8_BAR; PG8_SCHED;
.LBB0_630:
	s_add_i32 s67, s65, 2
	s_add_u32 s2, s0, 0xfffc0080
	s_addc_u32 s3, s1, -1
	s_add_i32 s99, 0, 0x10000
	s_cmp_eq_u32 s70, s65
	s_cselect_b32 vcc_hi, s55, s3
	s_cselect_b32 vcc_lo, s54, s2
	s_cselect_b32 s77, s45, s64
	s_cselect_b32 s76, s44, s63
	s_add_i32 s65, 0, 0x14000
	v_add_u32_e32 v142, s99, v180
	v_add_u32_e32 v158, s65, v180
	ds_read_b128 v[130:133], v142
	ds_read_b128 v[134:137], v142 offset:1024
	ds_read_b128 v[138:141], v142 offset:2048
	ds_read_b128 v[142:145], v142 offset:3072
	ds_read_b128 v[146:149], v158
	ds_read_b128 v[150:153], v158 offset:1024
	ds_read_b128 v[154:157], v158 offset:2048
	ds_read_b128 v[158:161], v158 offset:3072
	s_add_i32 m0, s53, 0xc000
	ds_read_b128 v[174:177], v191
	ds_read_b128 v[192:195], v191 offset:1024
	ds_read_b128 v[196:199], v191 offset:2048
	ds_read_b128 v[200:203], v191 offset:3072
	ds_read_b128 v[204:207], v191 offset:4096
	ds_read_b128 v[208:211], v191 offset:5120
	ds_read_b128 v[212:215], v191 offset:6144
	ds_read_b128 v[216:219], v191 offset:7168
	global_load_lds_dwordx4 v172, s[0:1]
	s_add_i32 m0, s53, 0xe000
	s_nop 0
	global_load_lds_dwordx4 v170, s[0:1]
	s_waitcnt vmcnt(8)
	s_waitcnt lgkmcnt(0)
	s_barrier
	s_setprio 1
	s_waitcnt lgkmcnt(0)
	v_mfma_f32_16x16x32_bf16 v[126:129], v[130:133], v[174:177], v[126:129]
	v_mfma_f32_16x16x32_bf16 v[122:125], v[138:141], v[174:177], v[122:125]
	v_mfma_f32_16x16x32_bf16 v[114:117], v[130:133], v[196:199], v[114:117]
	v_mfma_f32_16x16x32_bf16 v[106:109], v[138:141], v[196:199], v[106:109]
	v_mfma_f32_16x16x32_bf16 v[98:101], v[130:133], v[204:207], v[98:101]
	v_mfma_f32_16x16x32_bf16 v[90:93], v[138:141], v[204:207], v[90:93]
	v_mfma_f32_16x16x32_bf16 v[82:85], v[130:133], v[212:215], v[82:85]
	v_mfma_f32_16x16x32_bf16 v[74:77], v[138:141], v[212:215], v[74:77]
	v_mfma_f32_16x16x32_bf16 v[126:129], v[134:137], v[192:195], v[126:129]
	v_mfma_f32_16x16x32_bf16 v[122:125], v[142:145], v[192:195], v[122:125]
	v_mfma_f32_16x16x32_bf16 v[114:117], v[134:137], v[200:203], v[114:117]
	v_mfma_f32_16x16x32_bf16 v[106:109], v[142:145], v[200:203], v[106:109]
	v_mfma_f32_16x16x32_bf16 v[98:101], v[134:137], v[208:211], v[98:101]
	v_mfma_f32_16x16x32_bf16 v[90:93], v[142:145], v[208:211], v[90:93]
	v_mfma_f32_16x16x32_bf16 v[82:85], v[134:137], v[216:219], v[82:85]
	v_mfma_f32_16x16x32_bf16 v[74:77], v[142:145], v[216:219], v[74:77]
	s_setprio 0
	s_setprio 1
	v_mfma_f32_16x16x32_bf16 v[118:121], v[146:149], v[174:177], v[118:121]
	v_mfma_f32_16x16x32_bf16 v[110:113], v[154:157], v[174:177], v[110:113]
	v_mfma_f32_16x16x32_bf16 v[102:105], v[146:149], v[196:199], v[102:105]
	v_mfma_f32_16x16x32_bf16 v[94:97], v[154:157], v[196:199], v[94:97]
	v_mfma_f32_16x16x32_bf16 v[86:89], v[146:149], v[204:207], v[86:89]
	v_mfma_f32_16x16x32_bf16 v[78:81], v[154:157], v[204:207], v[78:81]
	v_mfma_f32_16x16x32_bf16 v[70:73], v[146:149], v[212:215], v[70:73]
	v_mfma_f32_16x16x32_bf16 v[66:69], v[154:157], v[212:215], v[66:69]
	v_mfma_f32_16x16x32_bf16 v[118:121], v[150:153], v[192:195], v[118:121]
	v_mfma_f32_16x16x32_bf16 v[110:113], v[158:161], v[192:195], v[110:113]
	v_mfma_f32_16x16x32_bf16 v[102:105], v[150:153], v[200:203], v[102:105]
	v_mfma_f32_16x16x32_bf16 v[94:97], v[158:161], v[200:203], v[94:97]
	s_setprio 2
	s_barrier
	v_mfma_f32_16x16x32_bf16 v[86:89], v[150:153], v[208:211], v[86:89]
	v_mfma_f32_16x16x32_bf16 v[78:81], v[158:161], v[208:211], v[78:81]
	v_mfma_f32_16x16x32_bf16 v[70:73], v[150:153], v[216:219], v[70:73]
	v_mfma_f32_16x16x32_bf16 v[66:69], v[158:161], v[216:219], v[66:69]
	s_setprio 0
	s_add_i32 s2, s99, s43
	s_mov_b32 m0, s2
	ds_read_b128 v[174:177], v191 offset:16384
	ds_read_b128 v[192:195], v191 offset:17408
	ds_read_b128 v[196:199], v191 offset:18432
	ds_read_b128 v[200:203], v191 offset:19456
	ds_read_b128 v[204:207], v191 offset:20480
	ds_read_b128 v[208:211], v191 offset:21504
	ds_read_b128 v[212:215], v191 offset:22528
	ds_read_b128 v[216:219], v191 offset:23552
	global_load_lds_dwordx4 v0, s[76:77]
	s_add_i32 m0, s2, 0x2000
	s_add_u32 s2, s76, 0x40000
	s_addc_u32 s3, s77, 0
	s_add_i32 s65, s65, s43
	global_load_lds_dwordx4 v168, s[76:77]
	s_mov_b32 m0, s65
	s_nop 0
	global_load_lds_dwordx4 v0, s[2:3]
	s_add_i32 m0, s65, 0x2000
	s_nop 0
	global_load_lds_dwordx4 v168, s[2:3]
	s_mov_b32 m0, s53
	s_nop 0
	global_load_lds_dwordx4 v164, vcc
	s_mov_b32 m0, s85
	s_nop 0
	global_load_lds_dwordx4 v166, vcc
	s_waitcnt vmcnt(8)
	s_waitcnt lgkmcnt(0)
	s_barrier
	s_setprio 1
	s_waitcnt lgkmcnt(0)
	v_mfma_f32_16x16x32_bf16 v[62:65], v[130:133], v[174:177], v[62:65]
	v_mfma_f32_16x16x32_bf16 v[58:61], v[138:141], v[174:177], v[58:61]
	v_mfma_f32_16x16x32_bf16 v[50:53], v[130:133], v[196:199], v[50:53]
	v_mfma_f32_16x16x32_bf16 v[42:45], v[138:141], v[196:199], v[42:45]
	v_mfma_f32_16x16x32_bf16 v[34:37], v[130:133], v[204:207], v[34:37]
	v_mfma_f32_16x16x32_bf16 v[26:29], v[138:141], v[204:207], v[26:29]
	v_mfma_f32_16x16x32_bf16 v[18:21], v[130:133], v[212:215], v[18:21]
	v_mfma_f32_16x16x32_bf16 v[10:13], v[138:141], v[212:215], v[10:13]
	v_mfma_f32_16x16x32_bf16 v[62:65], v[134:137], v[192:195], v[62:65]
	v_mfma_f32_16x16x32_bf16 v[58:61], v[142:145], v[192:195], v[58:61]
	v_mfma_f32_16x16x32_bf16 v[50:53], v[134:137], v[200:203], v[50:53]
	v_mfma_f32_16x16x32_bf16 v[42:45], v[142:145], v[200:203], v[42:45]
	v_mfma_f32_16x16x32_bf16 v[34:37], v[134:137], v[208:211], v[34:37]
	v_mfma_f32_16x16x32_bf16 v[26:29], v[142:145], v[208:211], v[26:29]
	v_mfma_f32_16x16x32_bf16 v[18:21], v[134:137], v[216:219], v[18:21]
	v_mfma_f32_16x16x32_bf16 v[10:13], v[142:145], v[216:219], v[10:13]
	s_setprio 0
	s_setprio 1
	v_mfma_f32_16x16x32_bf16 v[54:57], v[146:149], v[174:177], v[54:57]
	v_mfma_f32_16x16x32_bf16 v[46:49], v[154:157], v[174:177], v[46:49]
	v_mfma_f32_16x16x32_bf16 v[38:41], v[146:149], v[196:199], v[38:41]
	v_mfma_f32_16x16x32_bf16 v[30:33], v[154:157], v[196:199], v[30:33]
	v_mfma_f32_16x16x32_bf16 v[22:25], v[146:149], v[204:207], v[22:25]
	v_mfma_f32_16x16x32_bf16 v[14:17], v[154:157], v[204:207], v[14:17]
	v_mfma_f32_16x16x32_bf16 v[6:9], v[146:149], v[212:215], v[6:9]
	v_mfma_f32_16x16x32_bf16 v[2:5], v[154:157], v[212:215], v[2:5]
	v_mfma_f32_16x16x32_bf16 v[54:57], v[150:153], v[192:195], v[54:57]
	v_mfma_f32_16x16x32_bf16 v[46:49], v[158:161], v[192:195], v[46:49]
	v_mfma_f32_16x16x32_bf16 v[38:41], v[150:153], v[200:203], v[38:41]
	v_mfma_f32_16x16x32_bf16 v[30:33], v[158:161], v[200:203], v[30:33]
	s_setprio 2
	s_barrier
; #define PG8_STAGE(bufoff, gbase, voff) do { _Pragma("unroll") for (int _i = 0; _i < 2; ++_i) \
;         __builtin_amdgcn_global_load_lds((const unsigned*)((const char*)(gbase) + (voff)[_i]), (LAS unsigned*)(lds + (bufoff) + ldsw + _i * 8192), 16, 0, 0); } while (0)
; #define PG8_LDA(dst, b, h) do { _Pragma("unroll") for (int m = 0; m < 4; ++m) _Pragma("unroll") for (int k = 0; k < 2; ++k) dst[m][k] = *(const LAS bf16x8*)(lds + PG8_SA(b, h) + aoff + m * 2048 + k * 1024); } while (0)
; #define PG8_LDB(dst, b, h) do { _Pragma("unroll") for (int n = 0; n < 2; ++n) _Pragma("unroll") for (int k = 0; k < 2; ++k) dst[n][k] = *(const LAS bf16x8*)(lds + PG8_SB(b, h) + boff + n * 2048 + k * 1024); } while (0)
; #define PG8_MMA(ai, bj, At, Bt) do { __builtin_amdgcn_s_setprio(1); _Pragma("unroll") for (int m = 0; m < 4; ++m) _Pragma("unroll") for (int n = 0; n < 2; ++n) _Pragma("unroll") for (int k = 0; k < 2; ++k) \
;         acc[ai][bj][m][n] = __builtin_amdgcn_mfma_f32_16x16x32_bf16(Bt[n][k], At[m][k], acc[ai][bj][m][n], 0, 0, 0); __builtin_amdgcn_s_setprio(0); } while (0)
; #define PG8_WAIT_V(n) asm volatile("s_waitcnt vmcnt(" #n ")" ::: "memory")
; #define PG8_WAIT_L(n) asm volatile("s_waitcnt lgkmcnt(" #n ")" ::: "memory")
; #define PG8_BAR __builtin_amdgcn_s_barrier()
; #define PG8_SCHED __builtin_amdgcn_sched_barrier(0)
; template <class Epi, class Sched>
; __device__ __forceinline__ void gemm_phase(LAS unsigned char* lds, const Gemm g, Sched S, const Epi& E) {
;     ...
;             PG8_WAIT_V(8); PG8_WAIT_L(0); PG8_BAR; PG8_MMA(1, 0, At, B0); PG8_MMA(1, 1, At, B1); PG8_BAR; PG8_SCHED;
;             PG8_LDB(B0, 1, 0); PG8_LDB(B1, 1, 1); PG8_SCHED; PG8_LDA(At, 1, 0); PG8_STAGE(PG8_SA(0, 1), a2 + hstepA, voffA);
;             PG8_WAIT_V(8); PG8_WAIT_L(0); PG8_BAR; PG8_MMA(0, 0, At, B0); PG8_MMA(0, 1, At, B1); PG8_BAR; PG8_SCHED;
	v_mfma_f32_16x16x32_bf16 v[22:25], v[150:153], v[208:211], v[22:25]
	v_mfma_f32_16x16x32_bf16 v[14:17], v[158:161], v[208:211], v[14:17]
	v_mfma_f32_16x16x32_bf16 v[6:9], v[150:153], v[216:219], v[6:9]
	v_mfma_f32_16x16x32_bf16 v[2:5], v[158:161], v[216:219], v[2:5]
	s_setprio 0
	s_add_i32 s65, 0, 0x18000
	s_add_i32 s99, 0, 0x1c000
	v_add_u32_e32 v142, s65, v180
	v_add_u32_e32 v158, s99, v180
	ds_read_b128 v[130:133], v142
	ds_read_b128 v[134:137], v142 offset:1024
	ds_read_b128 v[138:141], v142 offset:2048
	ds_read_b128 v[142:145], v142 offset:3072
	ds_read_b128 v[146:149], v158
	ds_read_b128 v[150:153], v158 offset:1024
	ds_read_b128 v[154:157], v158 offset:2048
	ds_read_b128 v[158:161], v158 offset:3072
	s_add_u32 s2, vcc_lo, 0x40000
	s_addc_u32 s3, vcc_hi, 0
	s_mov_b32 m0, s18
	ds_read_b128 v[174:177], v191 offset:32768
	ds_read_b128 v[192:195], v191 offset:33792
	ds_read_b128 v[196:199], v191 offset:34816
	ds_read_b128 v[200:203], v191 offset:35840
	ds_read_b128 v[204:207], v191 offset:36864
	ds_read_b128 v[208:211], v191 offset:37888
	ds_read_b128 v[212:215], v191 offset:38912
	ds_read_b128 v[216:219], v191 offset:39936
	global_load_lds_dwordx4 v164, s[2:3]
	s_mov_b32 m0, s19
	s_nop 0
	global_load_lds_dwordx4 v166, s[2:3]
	s_waitcnt vmcnt(8)
	s_waitcnt lgkmcnt(0)
	s_barrier
	s_setprio 1
	s_waitcnt lgkmcnt(0)
	v_mfma_f32_16x16x32_bf16 v[126:129], v[130:133], v[174:177], v[126:129]
	v_mfma_f32_16x16x32_bf16 v[122:125], v[138:141], v[174:177], v[122:125]
	v_mfma_f32_16x16x32_bf16 v[114:117], v[130:133], v[196:199], v[114:117]
	v_mfma_f32_16x16x32_bf16 v[106:109], v[138:141], v[196:199], v[106:109]
	v_mfma_f32_16x16x32_bf16 v[98:101], v[130:133], v[204:207], v[98:101]
	v_mfma_f32_16x16x32_bf16 v[90:93], v[138:141], v[204:207], v[90:93]
	v_mfma_f32_16x16x32_bf16 v[82:85], v[130:133], v[212:215], v[82:85]
	v_mfma_f32_16x16x32_bf16 v[74:77], v[138:141], v[212:215], v[74:77]
	v_mfma_f32_16x16x32_bf16 v[126:129], v[134:137], v[192:195], v[126:129]
	v_mfma_f32_16x16x32_bf16 v[122:125], v[142:145], v[192:195], v[122:125]
	v_mfma_f32_16x16x32_bf16 v[114:117], v[134:137], v[200:203], v[114:117]
	v_mfma_f32_16x16x32_bf16 v[106:109], v[142:145], v[200:203], v[106:109]
	v_mfma_f32_16x16x32_bf16 v[98:101], v[134:137], v[208:211], v[98:101]
	v_mfma_f32_16x16x32_bf16 v[90:93], v[142:145], v[208:211], v[90:93]
	v_mfma_f32_16x16x32_bf16 v[82:85], v[134:137], v[216:219], v[82:85]
	v_mfma_f32_16x16x32_bf16 v[74:77], v[142:145], v[216:219], v[74:77]
	s_setprio 0
	s_setprio 1
	v_mfma_f32_16x16x32_bf16 v[118:121], v[146:149], v[174:177], v[118:121]
	v_mfma_f32_16x16x32_bf16 v[110:113], v[154:157], v[174:177], v[110:113]
	v_mfma_f32_16x16x32_bf16 v[102:105], v[146:149], v[196:199], v[102:105]
	v_mfma_f32_16x16x32_bf16 v[94:97], v[154:157], v[196:199], v[94:97]
	v_mfma_f32_16x16x32_bf16 v[86:89], v[146:149], v[204:207], v[86:89]
	v_mfma_f32_16x16x32_bf16 v[78:81], v[154:157], v[204:207], v[78:81]
	v_mfma_f32_16x16x32_bf16 v[70:73], v[146:149], v[212:215], v[70:73]
	v_mfma_f32_16x16x32_bf16 v[66:69], v[154:157], v[212:215], v[66:69]
	v_mfma_f32_16x16x32_bf16 v[118:121], v[150:153], v[192:195], v[118:121]
	v_mfma_f32_16x16x32_bf16 v[110:113], v[158:161], v[192:195], v[110:113]
	v_mfma_f32_16x16x32_bf16 v[102:105], v[150:153], v[200:203], v[102:105]
	v_mfma_f32_16x16x32_bf16 v[94:97], v[158:161], v[200:203], v[94:97]
	s_setprio 2
	s_barrier
; #define PG8_STAGE(bufoff, gbase, voff) do { _Pragma("unroll") for (int _i = 0; _i < 2; ++_i) \
;         __builtin_amdgcn_global_load_lds((const unsigned*)((const char*)(gbase) + (voff)[_i]), (LAS unsigned*)(lds + (bufoff) + ldsw + _i * 8192), 16, 0, 0); } while (0)
; #define PG8_LDA(dst, b, h) do { _Pragma("unroll") for (int m = 0; m < 4; ++m) _Pragma("unroll") for (int k = 0; k < 2; ++k) dst[m][k] = *(const LAS bf16x8*)(lds + PG8_SA(b, h) + aoff + m * 2048 + k * 1024); } while (0)
; #define PG8_MMA(ai, bj, At, Bt) do { __builtin_amdgcn_s_setprio(1); _Pragma("unroll") for (int m = 0; m < 4; ++m) _Pragma("unroll") for (int n = 0; n < 2; ++n) _Pragma("unroll") for (int k = 0; k < 2; ++k) \
;         acc[ai][bj][m][n] = __builtin_amdgcn_mfma_f32_16x16x32_bf16(Bt[n][k], At[m][k], acc[ai][bj][m][n], 0, 0, 0); __builtin_amdgcn_s_setprio(0); } while (0)
; #define PG8_WAIT_V(n) asm volatile("s_waitcnt vmcnt(" #n ")" ::: "memory")
; #define PG8_WAIT_L(n) asm volatile("s_waitcnt lgkmcnt(" #n ")" ::: "memory")
; #define PG8_BAR __builtin_amdgcn_s_barrier()
; #define PG8_SCHED __builtin_amdgcn_sched_barrier(0)
; template <class Epi, class Sched>
; __device__ __forceinline__ void gemm_phase(LAS unsigned char* lds, const Gemm g, Sched S, const Epi& E) {
;     ...
;             PG8_WAIT_V(8); PG8_WAIT_L(0); PG8_BAR; PG8_MMA(0, 0, At, B0); PG8_MMA(0, 1, At, B1); PG8_BAR; PG8_SCHED;
;             PG8_LDA(At, 1, 1); PG8_STAGE(PG8_SB(1, 0), b3, voffB); PG8_STAGE(PG8_SB(1, 1), b3 + hstepB, voffB); PG8_STAGE(PG8_SA(1, 0), a3, voffA);
;             PG8_WAIT_V(8); PG8_WAIT_L(0); PG8_BAR; PG8_MMA(1, 0, At, B0); PG8_MMA(1, 1, At, B1); PG8_BAR; PG8_SCHED;
;         }
;         if (wr == 0) PG8_BAR;
;         if (Epi::NEEDS_RS && E.ssq && has_next) {
	v_mfma_f32_16x16x32_bf16 v[86:89], v[150:153], v[208:211], v[86:89]
	v_mfma_f32_16x16x32_bf16 v[78:81], v[158:161], v[208:211], v[78:81]
	v_mfma_f32_16x16x32_bf16 v[70:73], v[150:153], v[216:219], v[70:73]
	v_mfma_f32_16x16x32_bf16 v[66:69], v[158:161], v[216:219], v[66:69]
	s_setprio 0
	s_add_i32 s2, s65, s43
	s_add_u32 s100, s76, 0x80
	s_addc_u32 s101, s77, 0
	s_mov_b32 m0, s2
	ds_read_b128 v[174:177], v191 offset:49152
	ds_read_b128 v[192:195], v191 offset:50176
	ds_read_b128 v[196:199], v191 offset:51200
	ds_read_b128 v[200:203], v191 offset:52224
	ds_read_b128 v[204:207], v191 offset:53248
	ds_read_b128 v[208:211], v191 offset:54272
	ds_read_b128 v[212:215], v191 offset:55296
	ds_read_b128 v[216:219], v191 offset:56320
	global_load_lds_dwordx4 v0, s[100:101]
	s_add_i32 m0, s2, 0x2000
	s_add_u32 s2, s76, 0x40080
	s_addc_u32 s3, s77, 0
	s_add_i32 s65, s99, s43
	global_load_lds_dwordx4 v168, s[100:101]
	s_mov_b32 m0, s65
	s_nop 0
	global_load_lds_dwordx4 v0, s[2:3]
	s_add_i32 m0, s65, 0x2000
	s_nop 0
	global_load_lds_dwordx4 v168, s[2:3]
	s_add_u32 s100, vcc_lo, 0x80
	s_addc_u32 s101, vcc_hi, 0
	s_mov_b32 m0, s71
	s_nop 0
	global_load_lds_dwordx4 v164, s[100:101]
	s_mov_b32 m0, s40
	s_nop 0
	global_load_lds_dwordx4 v166, s[100:101]
	s_waitcnt vmcnt(8)
	s_waitcnt lgkmcnt(0)
	s_barrier
	s_setprio 1
	s_waitcnt lgkmcnt(0)
	v_mfma_f32_16x16x32_bf16 v[62:65], v[130:133], v[174:177], v[62:65]
	v_mfma_f32_16x16x32_bf16 v[58:61], v[138:141], v[174:177], v[58:61]
	v_mfma_f32_16x16x32_bf16 v[50:53], v[130:133], v[196:199], v[50:53]
	v_mfma_f32_16x16x32_bf16 v[42:45], v[138:141], v[196:199], v[42:45]
	v_mfma_f32_16x16x32_bf16 v[34:37], v[130:133], v[204:207], v[34:37]
	v_mfma_f32_16x16x32_bf16 v[26:29], v[138:141], v[204:207], v[26:29]
	v_mfma_f32_16x16x32_bf16 v[18:21], v[130:133], v[212:215], v[18:21]
	v_mfma_f32_16x16x32_bf16 v[10:13], v[138:141], v[212:215], v[10:13]
	v_mfma_f32_16x16x32_bf16 v[62:65], v[134:137], v[192:195], v[62:65]
	v_mfma_f32_16x16x32_bf16 v[58:61], v[142:145], v[192:195], v[58:61]
	v_mfma_f32_16x16x32_bf16 v[50:53], v[134:137], v[200:203], v[50:53]
	v_mfma_f32_16x16x32_bf16 v[42:45], v[142:145], v[200:203], v[42:45]
	v_mfma_f32_16x16x32_bf16 v[34:37], v[134:137], v[208:211], v[34:37]
	v_mfma_f32_16x16x32_bf16 v[26:29], v[142:145], v[208:211], v[26:29]
	v_mfma_f32_16x16x32_bf16 v[18:21], v[134:137], v[216:219], v[18:21]
	v_mfma_f32_16x16x32_bf16 v[10:13], v[142:145], v[216:219], v[10:13]
	s_setprio 0
	s_setprio 1
	v_mfma_f32_16x16x32_bf16 v[54:57], v[146:149], v[174:177], v[54:57]
	v_mfma_f32_16x16x32_bf16 v[46:49], v[154:157], v[174:177], v[46:49]
	v_mfma_f32_16x16x32_bf16 v[38:41], v[146:149], v[196:199], v[38:41]
	v_mfma_f32_16x16x32_bf16 v[30:33], v[154:157], v[196:199], v[30:33]
	v_mfma_f32_16x16x32_bf16 v[22:25], v[146:149], v[204:207], v[22:25]
	v_mfma_f32_16x16x32_bf16 v[14:17], v[154:157], v[204:207], v[14:17]
	v_mfma_f32_16x16x32_bf16 v[6:9], v[146:149], v[212:215], v[6:9]
	v_mfma_f32_16x16x32_bf16 v[2:5], v[154:157], v[212:215], v[2:5]
	v_mfma_f32_16x16x32_bf16 v[54:57], v[150:153], v[192:195], v[54:57]
	v_mfma_f32_16x16x32_bf16 v[46:49], v[158:161], v[192:195], v[46:49]
	v_mfma_f32_16x16x32_bf16 v[38:41], v[150:153], v[200:203], v[38:41]
	v_mfma_f32_16x16x32_bf16 v[30:33], v[158:161], v[200:203], v[30:33]
	s_setprio 2
	s_barrier
	v_mfma_f32_16x16x32_bf16 v[22:25], v[150:153], v[208:211], v[22:25]
	v_mfma_f32_16x16x32_bf16 v[14:17], v[158:161], v[208:211], v[14:17]
	v_mfma_f32_16x16x32_bf16 v[6:9], v[150:153], v[216:219], v[6:9]
	v_mfma_f32_16x16x32_bf16 v[2:5], v[158:161], v[216:219], v[2:5]
	s_setprio 0
	s_add_u32 s63, s63, 0x100
	s_addc_u32 s64, s64, 0
	s_add_u32 s0, s0, 0x100
	s_addc_u32 s1, s1, 0
	s_cmp_ge_u32 s67, s58
	s_mov_b32 s65, s67
	s_cbranch_scc0 .LBB0_630
	s_and_b64 vcc, exec, s[94:95]
	s_cbranch_vccz .LBB0_635
	s_barrier
	s_and_b64 s[0:1], s[96:97], s[10:11]
	s_andn2_b64 vcc, exec, s[0:1]
	s_mov_b64 s[0:1], -1
	s_cbranch_vccnz .LBB0_636

; #define PG8_STAGE(bufoff, gbase, voff) do { _Pragma("unroll") for (int _i = 0; _i < 2; ++_i) \
;         __builtin_amdgcn_global_load_lds((const unsigned*)((const char*)(gbase) + (voff)[_i]), (LAS unsigned*)(lds + (bufoff) + ldsw + _i * 8192), 16, 0, 0); } while (0)
; #define PG8_LDA(dst, b, h) do { _Pragma("unroll") for (int m = 0; m < 4; ++m) _Pragma("unroll") for (int k = 0; k < 2; ++k) dst[m][k] = *(const LAS bf16x8*)(lds + PG8_SA(b, h) + aoff + m * 2048 + k * 1024); } while (0)
; #define PG8_LDB(dst, b, h) do { _Pragma("unroll") for (int n = 0; n < 2; ++n) _Pragma("unroll") for (int k = 0; k < 2; ++k) dst[n][k] = *(const LAS bf16x8*)(lds + PG8_SB(b, h) + boff + n * 2048 + k * 1024); } while (0)
; #define PG8_MMA(ai, bj, At, Bt) do { __builtin_amdgcn_s_setprio(1); _Pragma("unroll") for (int m = 0; m < 4; ++m) _Pragma("unroll") for (int n = 0; n < 2; ++n) _Pragma("unroll") for (int k = 0; k < 2; ++k) \
;         acc[ai][bj][m][n] = __builtin_amdgcn_mfma_f32_16x16x32_bf16(Bt[n][k], At[m][k], acc[ai][bj][m][n], 0, 0, 0); __builtin_amdgcn_s_setprio(0); } while (0)
; #define PG8_WAIT_V(n) asm volatile("s_waitcnt vmcnt(" #n ")" ::: "memory")
; #define PG8_WAIT_L(n) asm volatile("s_waitcnt lgkmcnt(" #n ")" ::: "memory")
; #define PG8_BAR __builtin_amdgcn_s_barrier()
; #define PG8_SCHED __builtin_amdgcn_sched_barrier(0)
; template <class Epi, class Sched>
; __device__ __forceinline__ void gemm_phase(LAS unsigned char* lds, const Gemm g, Sched S, const Epi& E) {
;     ...
;         for (int t = 0; t < nt; t += 2) {
;             const bool last = (t == nt - 2);
;             const char* a1 = cA + (size_t)(t + 1) * kstep;
;             const char* a2 = last ? nA : cA + (size_t)(t + 2) * kstep; const char* b2 = last ? nB : cB + (size_t)(t + 2) * kstep;
;             const char* a3 = a2 + kstep; const char* b3 = b2 + kstep;
;             PG8_LDB(B0, 0, 0); PG8_LDB(B1, 0, 1); PG8_SCHED; PG8_LDA(At, 0, 0); PG8_STAGE(PG8_SA(1, 1), a1 + hstepA, voffA);
;             PG8_WAIT_V(8); PG8_WAIT_L(0); PG8_BAR; PG8_MMA(0, 0, At, B0); PG8_MMA(0, 1, At, B1); PG8_BAR; PG8_SCHED;
;             PG8_LDA(At, 0, 1); PG8_STAGE(PG8_SB(0, 0), b2, voffB); PG8_STAGE(PG8_SB(0, 1), b2 + hstepB, voffB); PG8_STAGE(PG8_SA(0, 0), a2, voffA);
;             PG8_WAIT_V(8); PG8_WAIT_L(0); PG8_BAR; PG8_MMA(1, 0, At, B0); PG8_MMA(1, 1, At, B1); PG8_BAR; PG8_SCHED;
.LBB0_727:
	s_add_i32 s21, s20, 2
	s_add_u32 s3, s42, 0x80
	s_addc_u32 s35, s43, 0
	s_add_i32 s52, 0, 0x10000
	s_cmp_eq_u32 s99, s20
	s_cselect_b32 s45, s89, s35
	s_cselect_b32 s44, s88, s3
	s_cselect_b32 s41, s91, s19
	s_cselect_b32 s40, s90, s11
	s_add_i32 s3, 0, 0x14000
	v_add_u32_e32 v126, s52, v192
	v_add_u32_e32 v170, s3, v192
	ds_read_b128 v[114:117], v126
	ds_read_b128 v[118:121], v126 offset:1024
	ds_read_b128 v[122:125], v126 offset:2048
	ds_read_b128 v[126:129], v126 offset:3072
	ds_read_b128 v[130:133], v170
	ds_read_b128 v[134:137], v170 offset:1024
	ds_read_b128 v[166:169], v170 offset:2048
	ds_read_b128 v[170:173], v170 offset:3072
	s_add_i32 m0, s85, 0xc000
	ds_read_b128 v[174:177], v194
	ds_read_b128 v[178:181], v194 offset:1024
	ds_read_b128 v[196:199], v194 offset:2048
	ds_read_b128 v[200:203], v194 offset:3072
	ds_read_b128 v[204:207], v194 offset:4096
	ds_read_b128 v[208:211], v194 offset:5120
	ds_read_b128 v[212:215], v194 offset:6144
	ds_read_b128 v[216:219], v194 offset:7168
	global_load_lds_dwordx4 v164, s[42:43]
	s_add_i32 m0, s85, 0xe000
	s_nop 0
	global_load_lds_dwordx4 v160, s[42:43]
	s_waitcnt vmcnt(8)
	s_waitcnt lgkmcnt(0)
	s_barrier
	s_setprio 1
	s_waitcnt lgkmcnt(0)
	v_mfma_f32_16x16x32_bf16 v[150:153], v[114:117], v[174:177], v[150:153]
	v_mfma_f32_16x16x32_bf16 v[146:149], v[122:125], v[174:177], v[146:149]
	v_mfma_f32_16x16x32_bf16 v[110:113], v[114:117], v[196:199], v[110:113]
	v_mfma_f32_16x16x32_bf16 v[106:109], v[122:125], v[196:199], v[106:109]
	v_mfma_f32_16x16x32_bf16 v[94:97], v[114:117], v[204:207], v[94:97]
	v_mfma_f32_16x16x32_bf16 v[90:93], v[122:125], v[204:207], v[90:93]
	v_mfma_f32_16x16x32_bf16 v[78:81], v[114:117], v[212:215], v[78:81]
	v_mfma_f32_16x16x32_bf16 v[74:77], v[122:125], v[212:215], v[74:77]
	v_mfma_f32_16x16x32_bf16 v[150:153], v[118:121], v[178:181], v[150:153]
	v_mfma_f32_16x16x32_bf16 v[146:149], v[126:129], v[178:181], v[146:149]
	v_mfma_f32_16x16x32_bf16 v[110:113], v[118:121], v[200:203], v[110:113]
	v_mfma_f32_16x16x32_bf16 v[106:109], v[126:129], v[200:203], v[106:109]
	v_mfma_f32_16x16x32_bf16 v[94:97], v[118:121], v[208:211], v[94:97]
	v_mfma_f32_16x16x32_bf16 v[90:93], v[126:129], v[208:211], v[90:93]
	v_mfma_f32_16x16x32_bf16 v[78:81], v[118:121], v[216:219], v[78:81]
	v_mfma_f32_16x16x32_bf16 v[74:77], v[126:129], v[216:219], v[74:77]
	s_setprio 0
	s_setprio 1
	v_mfma_f32_16x16x32_bf16 v[142:145], v[130:133], v[174:177], v[142:145]
	v_mfma_f32_16x16x32_bf16 v[138:141], v[166:169], v[174:177], v[138:141]
	v_mfma_f32_16x16x32_bf16 v[102:105], v[130:133], v[196:199], v[102:105]
	v_mfma_f32_16x16x32_bf16 v[98:101], v[166:169], v[196:199], v[98:101]
	v_mfma_f32_16x16x32_bf16 v[86:89], v[130:133], v[204:207], v[86:89]
	v_mfma_f32_16x16x32_bf16 v[82:85], v[166:169], v[204:207], v[82:85]
	v_mfma_f32_16x16x32_bf16 v[70:73], v[130:133], v[212:215], v[70:73]
	v_mfma_f32_16x16x32_bf16 v[66:69], v[166:169], v[212:215], v[66:69]
	v_mfma_f32_16x16x32_bf16 v[142:145], v[134:137], v[178:181], v[142:145]
	v_mfma_f32_16x16x32_bf16 v[138:141], v[170:173], v[178:181], v[138:141]
	v_mfma_f32_16x16x32_bf16 v[102:105], v[134:137], v[200:203], v[102:105]
	v_mfma_f32_16x16x32_bf16 v[98:101], v[170:173], v[200:203], v[98:101]
	s_setprio 2
	s_barrier
	v_mfma_f32_16x16x32_bf16 v[86:89], v[134:137], v[208:211], v[86:89]
	v_mfma_f32_16x16x32_bf16 v[82:85], v[170:173], v[208:211], v[82:85]
	v_mfma_f32_16x16x32_bf16 v[70:73], v[134:137], v[216:219], v[70:73]
	v_mfma_f32_16x16x32_bf16 v[66:69], v[170:173], v[216:219], v[66:69]
	s_setprio 0
	s_add_i32 s20, s52, s77
	s_add_u32 s100, s40, 0x80
	s_addc_u32 s101, s41, 0
	s_mov_b32 m0, s20
	ds_read_b128 v[174:177], v194 offset:16384
	ds_read_b128 v[178:181], v194 offset:17408
	ds_read_b128 v[196:199], v194 offset:18432
	ds_read_b128 v[200:203], v194 offset:19456
	ds_read_b128 v[204:207], v194 offset:20480
	ds_read_b128 v[208:211], v194 offset:21504
	ds_read_b128 v[212:215], v194 offset:22528
	ds_read_b128 v[216:219], v194 offset:23552
	global_load_lds_dwordx4 v0, s[40:41]
	s_add_i32 m0, s20, 0x2000
	s_add_i32 s3, s3, s77
	global_load_lds_dwordx4 v158, s[40:41]
	s_add_u32 s40, s40, s24
	s_addc_u32 s41, s41, s25
	s_mov_b32 m0, s3
	s_nop 0
	global_load_lds_dwordx4 v0, s[40:41]
	s_add_i32 m0, s3, 0x2000
	s_nop 0
	global_load_lds_dwordx4 v158, s[40:41]
	s_mov_b32 m0, s85
	s_nop 0
	global_load_lds_dwordx4 v154, s[44:45]
	s_mov_b32 m0, s92
	s_nop 0
	global_load_lds_dwordx4 v156, s[44:45]
	s_waitcnt vmcnt(8)
	s_waitcnt lgkmcnt(0)
	s_barrier
	s_setprio 1
	s_waitcnt lgkmcnt(0)
	v_mfma_f32_16x16x32_bf16 v[62:65], v[114:117], v[174:177], v[62:65]
	v_mfma_f32_16x16x32_bf16 v[58:61], v[122:125], v[174:177], v[58:61]
	v_mfma_f32_16x16x32_bf16 v[46:49], v[114:117], v[196:199], v[46:49]
	v_mfma_f32_16x16x32_bf16 v[42:45], v[122:125], v[196:199], v[42:45]
	v_mfma_f32_16x16x32_bf16 v[30:33], v[114:117], v[204:207], v[30:33]
	v_mfma_f32_16x16x32_bf16 v[26:29], v[122:125], v[204:207], v[26:29]
	v_mfma_f32_16x16x32_bf16 v[14:17], v[114:117], v[212:215], v[14:17]
	v_mfma_f32_16x16x32_bf16 v[10:13], v[122:125], v[212:215], v[10:13]
	v_mfma_f32_16x16x32_bf16 v[62:65], v[118:121], v[178:181], v[62:65]
	v_mfma_f32_16x16x32_bf16 v[58:61], v[126:129], v[178:181], v[58:61]
	v_mfma_f32_16x16x32_bf16 v[46:49], v[118:121], v[200:203], v[46:49]
	v_mfma_f32_16x16x32_bf16 v[42:45], v[126:129], v[200:203], v[42:45]
	v_mfma_f32_16x16x32_bf16 v[30:33], v[118:121], v[208:211], v[30:33]
	v_mfma_f32_16x16x32_bf16 v[26:29], v[126:129], v[208:211], v[26:29]
	v_mfma_f32_16x16x32_bf16 v[14:17], v[118:121], v[216:219], v[14:17]
	v_mfma_f32_16x16x32_bf16 v[10:13], v[126:129], v[216:219], v[10:13]
	s_setprio 0
	s_setprio 1
	v_mfma_f32_16x16x32_bf16 v[54:57], v[130:133], v[174:177], v[54:57]
	v_mfma_f32_16x16x32_bf16 v[50:53], v[166:169], v[174:177], v[50:53]
	v_mfma_f32_16x16x32_bf16 v[38:41], v[130:133], v[196:199], v[38:41]
	v_mfma_f32_16x16x32_bf16 v[34:37], v[166:169], v[196:199], v[34:37]
	v_mfma_f32_16x16x32_bf16 v[22:25], v[130:133], v[204:207], v[22:25]
	v_mfma_f32_16x16x32_bf16 v[18:21], v[166:169], v[204:207], v[18:21]
	v_mfma_f32_16x16x32_bf16 v[6:9], v[130:133], v[212:215], v[6:9]
	v_mfma_f32_16x16x32_bf16 v[2:5], v[166:169], v[212:215], v[2:5]
	v_mfma_f32_16x16x32_bf16 v[54:57], v[134:137], v[178:181], v[54:57]
	v_mfma_f32_16x16x32_bf16 v[50:53], v[170:173], v[178:181], v[50:53]
	v_mfma_f32_16x16x32_bf16 v[38:41], v[134:137], v[200:203], v[38:41]
	v_mfma_f32_16x16x32_bf16 v[34:37], v[170:173], v[200:203], v[34:37]
	s_setprio 2
	s_barrier
; #define PG8_STAGE(bufoff, gbase, voff) do { _Pragma("unroll") for (int _i = 0; _i < 2; ++_i) \
;         __builtin_amdgcn_global_load_lds((const unsigned*)((const char*)(gbase) + (voff)[_i]), (LAS unsigned*)(lds + (bufoff) + ldsw + _i * 8192), 16, 0, 0); } while (0)
; #define PG8_LDA(dst, b, h) do { _Pragma("unroll") for (int m = 0; m < 4; ++m) _Pragma("unroll") for (int k = 0; k < 2; ++k) dst[m][k] = *(const LAS bf16x8*)(lds + PG8_SA(b, h) + aoff + m * 2048 + k * 1024); } while (0)
; #define PG8_LDB(dst, b, h) do { _Pragma("unroll") for (int n = 0; n < 2; ++n) _Pragma("unroll") for (int k = 0; k < 2; ++k) dst[n][k] = *(const LAS bf16x8*)(lds + PG8_SB(b, h) + boff + n * 2048 + k * 1024); } while (0)
; #define PG8_MMA(ai, bj, At, Bt) do { __builtin_amdgcn_s_setprio(1); _Pragma("unroll") for (int m = 0; m < 4; ++m) _Pragma("unroll") for (int n = 0; n < 2; ++n) _Pragma("unroll") for (int k = 0; k < 2; ++k) \
;         acc[ai][bj][m][n] = __builtin_amdgcn_mfma_f32_16x16x32_bf16(Bt[n][k], At[m][k], acc[ai][bj][m][n], 0, 0, 0); __builtin_amdgcn_s_setprio(0); } while (0)
; #define PG8_WAIT_V(n) asm volatile("s_waitcnt vmcnt(" #n ")" ::: "memory")
; #define PG8_WAIT_L(n) asm volatile("s_waitcnt lgkmcnt(" #n ")" ::: "memory")
; #define PG8_BAR __builtin_amdgcn_s_barrier()
; #define PG8_SCHED __builtin_amdgcn_sched_barrier(0)
; template <class Epi, class Sched>
; __device__ __forceinline__ void gemm_phase(LAS unsigned char* lds, const Gemm g, Sched S, const Epi& E) {
;     ...
;             PG8_WAIT_V(8); PG8_WAIT_L(0); PG8_BAR; PG8_MMA(1, 0, At, B0); PG8_MMA(1, 1, At, B1); PG8_BAR; PG8_SCHED;
;             PG8_LDB(B0, 1, 0); PG8_LDB(B1, 1, 1); PG8_SCHED; PG8_LDA(At, 1, 0); PG8_STAGE(PG8_SA(0, 1), a2 + hstepA, voffA);
;             PG8_WAIT_V(8); PG8_WAIT_L(0); PG8_BAR; PG8_MMA(0, 0, At, B0); PG8_MMA(0, 1, At, B1); PG8_BAR; PG8_SCHED;
	v_mfma_f32_16x16x32_bf16 v[22:25], v[134:137], v[208:211], v[22:25]
	v_mfma_f32_16x16x32_bf16 v[18:21], v[170:173], v[208:211], v[18:21]
	v_mfma_f32_16x16x32_bf16 v[6:9], v[134:137], v[216:219], v[6:9]
	v_mfma_f32_16x16x32_bf16 v[2:5], v[170:173], v[216:219], v[2:5]
	s_setprio 0
	s_add_i32 s3, 0, 0x18000
	s_add_i32 s20, 0, 0x1c000
	v_add_u32_e32 v126, s3, v192
	v_add_u32_e32 v170, s20, v192
	ds_read_b128 v[114:117], v126
	ds_read_b128 v[118:121], v126 offset:1024
	ds_read_b128 v[122:125], v126 offset:2048
	ds_read_b128 v[126:129], v126 offset:3072
	ds_read_b128 v[130:133], v170
	ds_read_b128 v[134:137], v170 offset:1024
	ds_read_b128 v[166:169], v170 offset:2048
	ds_read_b128 v[170:173], v170 offset:3072
	s_add_u32 s40, s44, s8
	s_addc_u32 s41, s45, 0
	s_mov_b32 m0, s93
	ds_read_b128 v[174:177], v194 offset:32768
	ds_read_b128 v[178:181], v194 offset:33792
	ds_read_b128 v[196:199], v194 offset:34816
	ds_read_b128 v[200:203], v194 offset:35840
	ds_read_b128 v[204:207], v194 offset:36864
	ds_read_b128 v[208:211], v194 offset:37888
	ds_read_b128 v[212:215], v194 offset:38912
	ds_read_b128 v[216:219], v194 offset:39936
	global_load_lds_dwordx4 v154, s[40:41]
	s_mov_b32 m0, s94
	s_nop 0
	global_load_lds_dwordx4 v156, s[40:41]
	s_waitcnt vmcnt(8)
	s_waitcnt lgkmcnt(0)
	s_barrier
	s_setprio 1
	s_waitcnt lgkmcnt(0)
	v_mfma_f32_16x16x32_bf16 v[150:153], v[114:117], v[174:177], v[150:153]
	v_mfma_f32_16x16x32_bf16 v[146:149], v[122:125], v[174:177], v[146:149]
	v_mfma_f32_16x16x32_bf16 v[110:113], v[114:117], v[196:199], v[110:113]
	v_mfma_f32_16x16x32_bf16 v[106:109], v[122:125], v[196:199], v[106:109]
	v_mfma_f32_16x16x32_bf16 v[94:97], v[114:117], v[204:207], v[94:97]
	v_mfma_f32_16x16x32_bf16 v[90:93], v[122:125], v[204:207], v[90:93]
	v_mfma_f32_16x16x32_bf16 v[78:81], v[114:117], v[212:215], v[78:81]
	v_mfma_f32_16x16x32_bf16 v[74:77], v[122:125], v[212:215], v[74:77]
	v_mfma_f32_16x16x32_bf16 v[150:153], v[118:121], v[178:181], v[150:153]
	v_mfma_f32_16x16x32_bf16 v[146:149], v[126:129], v[178:181], v[146:149]
	v_mfma_f32_16x16x32_bf16 v[110:113], v[118:121], v[200:203], v[110:113]
	v_mfma_f32_16x16x32_bf16 v[106:109], v[126:129], v[200:203], v[106:109]
	v_mfma_f32_16x16x32_bf16 v[94:97], v[118:121], v[208:211], v[94:97]
	v_mfma_f32_16x16x32_bf16 v[90:93], v[126:129], v[208:211], v[90:93]
	v_mfma_f32_16x16x32_bf16 v[78:81], v[118:121], v[216:219], v[78:81]
	v_mfma_f32_16x16x32_bf16 v[74:77], v[126:129], v[216:219], v[74:77]
	s_setprio 0
	s_setprio 1
	v_mfma_f32_16x16x32_bf16 v[142:145], v[130:133], v[174:177], v[142:145]
	v_mfma_f32_16x16x32_bf16 v[138:141], v[166:169], v[174:177], v[138:141]
	v_mfma_f32_16x16x32_bf16 v[102:105], v[130:133], v[196:199], v[102:105]
	v_mfma_f32_16x16x32_bf16 v[98:101], v[166:169], v[196:199], v[98:101]
	v_mfma_f32_16x16x32_bf16 v[86:89], v[130:133], v[204:207], v[86:89]
	v_mfma_f32_16x16x32_bf16 v[82:85], v[166:169], v[204:207], v[82:85]
	v_mfma_f32_16x16x32_bf16 v[70:73], v[130:133], v[212:215], v[70:73]
	v_mfma_f32_16x16x32_bf16 v[66:69], v[166:169], v[212:215], v[66:69]
	v_mfma_f32_16x16x32_bf16 v[142:145], v[134:137], v[178:181], v[142:145]
	v_mfma_f32_16x16x32_bf16 v[138:141], v[170:173], v[178:181], v[138:141]
	v_mfma_f32_16x16x32_bf16 v[102:105], v[134:137], v[200:203], v[102:105]
	v_mfma_f32_16x16x32_bf16 v[98:101], v[170:173], v[200:203], v[98:101]
	s_setprio 2
	s_barrier
; #define PG8_STAGE(bufoff, gbase, voff) do { _Pragma("unroll") for (int _i = 0; _i < 2; ++_i) \
;         __builtin_amdgcn_global_load_lds((const unsigned*)((const char*)(gbase) + (voff)[_i]), (LAS unsigned*)(lds + (bufoff) + ldsw + _i * 8192), 16, 0, 0); } while (0)
; #define PG8_LDA(dst, b, h) do { _Pragma("unroll") for (int m = 0; m < 4; ++m) _Pragma("unroll") for (int k = 0; k < 2; ++k) dst[m][k] = *(const LAS bf16x8*)(lds + PG8_SA(b, h) + aoff + m * 2048 + k * 1024); } while (0)
; #define PG8_MMA(ai, bj, At, Bt) do { __builtin_amdgcn_s_setprio(1); _Pragma("unroll") for (int m = 0; m < 4; ++m) _Pragma("unroll") for (int n = 0; n < 2; ++n) _Pragma("unroll") for (int k = 0; k < 2; ++k) \
;         acc[ai][bj][m][n] = __builtin_amdgcn_mfma_f32_16x16x32_bf16(Bt[n][k], At[m][k], acc[ai][bj][m][n], 0, 0, 0); __builtin_amdgcn_s_setprio(0); } while (0)
; #define PG8_WAIT_V(n) asm volatile("s_waitcnt vmcnt(" #n ")" ::: "memory")
; #define PG8_WAIT_L(n) asm volatile("s_waitcnt lgkmcnt(" #n ")" ::: "memory")
; #define PG8_BAR __builtin_amdgcn_s_barrier()
; #define PG8_SCHED __builtin_amdgcn_sched_barrier(0)
; template <class Epi, class Sched>
; __device__ __forceinline__ void gemm_phase(LAS unsigned char* lds, const Gemm g, Sched S, const Epi& E) {
;     ...
;             PG8_WAIT_V(8); PG8_WAIT_L(0); PG8_BAR; PG8_MMA(0, 0, At, B0); PG8_MMA(0, 1, At, B1); PG8_BAR; PG8_SCHED;
;             PG8_LDA(At, 1, 1); PG8_STAGE(PG8_SB(1, 0), b3, voffB); PG8_STAGE(PG8_SB(1, 1), b3 + hstepB, voffB); PG8_STAGE(PG8_SA(1, 0), a3, voffA);
;             PG8_WAIT_V(8); PG8_WAIT_L(0); PG8_BAR; PG8_MMA(1, 0, At, B0); PG8_MMA(1, 1, At, B1); PG8_BAR; PG8_SCHED;
;         }
;         if (wr == 0) PG8_BAR;
;         if (Epi::NEEDS_RS && E.ssq && has_next) {
	v_mfma_f32_16x16x32_bf16 v[86:89], v[134:137], v[208:211], v[86:89]
	v_mfma_f32_16x16x32_bf16 v[82:85], v[170:173], v[208:211], v[82:85]
	v_mfma_f32_16x16x32_bf16 v[70:73], v[134:137], v[216:219], v[70:73]
	v_mfma_f32_16x16x32_bf16 v[66:69], v[170:173], v[216:219], v[66:69]
	s_setprio 0
	s_add_i32 s3, s3, s77
	s_mov_b32 m0, s3
	ds_read_b128 v[174:177], v194 offset:49152
	ds_read_b128 v[178:181], v194 offset:50176
	ds_read_b128 v[196:199], v194 offset:51200
	ds_read_b128 v[200:203], v194 offset:52224
	ds_read_b128 v[204:207], v194 offset:53248
	ds_read_b128 v[208:211], v194 offset:54272
	ds_read_b128 v[212:215], v194 offset:55296
	ds_read_b128 v[216:219], v194 offset:56320
	global_load_lds_dwordx4 v0, s[100:101]
	s_add_i32 m0, s3, 0x2000
	s_add_i32 s3, s20, s77
	global_load_lds_dwordx4 v158, s[100:101]
	s_add_u32 s100, s100, s24
	s_addc_u32 s101, s101, s25
	s_mov_b32 m0, s3
	s_nop 0
	global_load_lds_dwordx4 v0, s[100:101]
	s_add_i32 m0, s3, 0x2000
	s_nop 0
	global_load_lds_dwordx4 v158, s[100:101]
	s_add_u32 s100, s44, 0x80
	s_addc_u32 s101, s45, 0
	s_mov_b32 m0, s97
	s_nop 0
	global_load_lds_dwordx4 v154, s[100:101]
	s_mov_b32 m0, s98
	s_nop 0
	global_load_lds_dwordx4 v156, s[100:101]
	s_waitcnt vmcnt(8)
	s_waitcnt lgkmcnt(0)
	s_barrier
	s_setprio 1
	s_waitcnt lgkmcnt(0)
	v_mfma_f32_16x16x32_bf16 v[62:65], v[114:117], v[174:177], v[62:65]
	v_mfma_f32_16x16x32_bf16 v[58:61], v[122:125], v[174:177], v[58:61]
	v_mfma_f32_16x16x32_bf16 v[46:49], v[114:117], v[196:199], v[46:49]
	v_mfma_f32_16x16x32_bf16 v[42:45], v[122:125], v[196:199], v[42:45]
	v_mfma_f32_16x16x32_bf16 v[30:33], v[114:117], v[204:207], v[30:33]
	v_mfma_f32_16x16x32_bf16 v[26:29], v[122:125], v[204:207], v[26:29]
	v_mfma_f32_16x16x32_bf16 v[14:17], v[114:117], v[212:215], v[14:17]
	v_mfma_f32_16x16x32_bf16 v[10:13], v[122:125], v[212:215], v[10:13]
	v_mfma_f32_16x16x32_bf16 v[62:65], v[118:121], v[178:181], v[62:65]
	v_mfma_f32_16x16x32_bf16 v[58:61], v[126:129], v[178:181], v[58:61]
	v_mfma_f32_16x16x32_bf16 v[46:49], v[118:121], v[200:203], v[46:49]
	v_mfma_f32_16x16x32_bf16 v[42:45], v[126:129], v[200:203], v[42:45]
	v_mfma_f32_16x16x32_bf16 v[30:33], v[118:121], v[208:211], v[30:33]
	v_mfma_f32_16x16x32_bf16 v[26:29], v[126:129], v[208:211], v[26:29]
	v_mfma_f32_16x16x32_bf16 v[14:17], v[118:121], v[216:219], v[14:17]
	v_mfma_f32_16x16x32_bf16 v[10:13], v[126:129], v[216:219], v[10:13]
	s_setprio 0
	s_setprio 1
	v_mfma_f32_16x16x32_bf16 v[54:57], v[130:133], v[174:177], v[54:57]
	v_mfma_f32_16x16x32_bf16 v[50:53], v[166:169], v[174:177], v[50:53]
	v_mfma_f32_16x16x32_bf16 v[38:41], v[130:133], v[196:199], v[38:41]
	v_mfma_f32_16x16x32_bf16 v[34:37], v[166:169], v[196:199], v[34:37]
	v_mfma_f32_16x16x32_bf16 v[22:25], v[130:133], v[204:207], v[22:25]
	v_mfma_f32_16x16x32_bf16 v[18:21], v[166:169], v[204:207], v[18:21]
	v_mfma_f32_16x16x32_bf16 v[6:9], v[130:133], v[212:215], v[6:9]
	v_mfma_f32_16x16x32_bf16 v[2:5], v[166:169], v[212:215], v[2:5]
	v_mfma_f32_16x16x32_bf16 v[54:57], v[134:137], v[178:181], v[54:57]
	v_mfma_f32_16x16x32_bf16 v[50:53], v[170:173], v[178:181], v[50:53]
	v_mfma_f32_16x16x32_bf16 v[38:41], v[134:137], v[200:203], v[38:41]
	v_mfma_f32_16x16x32_bf16 v[34:37], v[170:173], v[200:203], v[34:37]
	s_setprio 2
	s_barrier
	v_mfma_f32_16x16x32_bf16 v[22:25], v[134:137], v[208:211], v[22:25]
	v_mfma_f32_16x16x32_bf16 v[18:21], v[170:173], v[208:211], v[18:21]
	v_mfma_f32_16x16x32_bf16 v[6:9], v[134:137], v[216:219], v[6:9]
	v_mfma_f32_16x16x32_bf16 v[2:5], v[170:173], v[216:219], v[2:5]
	s_setprio 0
	s_add_u32 s11, s11, 0x100
	s_addc_u32 s19, s19, 0
	s_add_u32 s42, s42, 0x100
	s_addc_u32 s43, s43, 0
	s_cmp_ge_u32 s21, s96
	s_mov_b32 s20, s21
	s_cbranch_scc0 .LBB0_727
	s_and_b64 vcc, exec, s[30:31]
	s_cbranch_vccz .LBB0_730
	s_barrier

; #define PG8_STAGE(bufoff, gbase, voff) do { _Pragma("unroll") for (int _i = 0; _i < 2; ++_i) \
;         __builtin_amdgcn_global_load_lds((const unsigned*)((const char*)(gbase) + (voff)[_i]), (LAS unsigned*)(lds + (bufoff) + ldsw + _i * 8192), 16, 0, 0); } while (0)
; #define PG8_LDA(dst, b, h) do { _Pragma("unroll") for (int m = 0; m < 4; ++m) _Pragma("unroll") for (int k = 0; k < 2; ++k) dst[m][k] = *(const LAS bf16x8*)(lds + PG8_SA(b, h) + aoff + m * 2048 + k * 1024); } while (0)
; #define PG8_LDB(dst, b, h) do { _Pragma("unroll") for (int n = 0; n < 2; ++n) _Pragma("unroll") for (int k = 0; k < 2; ++k) dst[n][k] = *(const LAS bf16x8*)(lds + PG8_SB(b, h) + boff + n * 2048 + k * 1024); } while (0)
; #define PG8_MMA(ai, bj, At, Bt) do { __builtin_amdgcn_s_setprio(1); _Pragma("unroll") for (int m = 0; m < 4; ++m) _Pragma("unroll") for (int n = 0; n < 2; ++n) _Pragma("unroll") for (int k = 0; k < 2; ++k) \
;         acc[ai][bj][m][n] = __builtin_amdgcn_mfma_f32_16x16x32_bf16(Bt[n][k], At[m][k], acc[ai][bj][m][n], 0, 0, 0); __builtin_amdgcn_s_setprio(0); } while (0)
; #define PG8_WAIT_V(n) asm volatile("s_waitcnt vmcnt(" #n ")" ::: "memory")
; #define PG8_WAIT_L(n) asm volatile("s_waitcnt lgkmcnt(" #n ")" ::: "memory")
; #define PG8_BAR __builtin_amdgcn_s_barrier()
; #define PG8_SCHED __builtin_amdgcn_sched_barrier(0)
; template <class Epi, class Sched>
; __device__ __forceinline__ void gemm_phase(LAS unsigned char* lds, const Gemm g, Sched S, const Epi& E) {
;     ...
;         for (int t = 0; t < nt; t += 2) {
;             const bool last = (t == nt - 2);
;             const char* a1 = cA + (size_t)(t + 1) * kstep;
;             const char* a2 = last ? nA : cA + (size_t)(t + 2) * kstep; const char* b2 = last ? nB : cB + (size_t)(t + 2) * kstep;
;             const char* a3 = a2 + kstep; const char* b3 = b2 + kstep;
;             PG8_LDB(B0, 0, 0); PG8_LDB(B1, 0, 1); PG8_SCHED; PG8_LDA(At, 0, 0); PG8_STAGE(PG8_SA(1, 1), a1 + hstepA, voffA);
;             PG8_WAIT_V(8); PG8_WAIT_L(0); PG8_BAR; PG8_MMA(0, 0, At, B0); PG8_MMA(0, 1, At, B1); PG8_BAR; PG8_SCHED;
;             PG8_LDA(At, 0, 1); PG8_STAGE(PG8_SB(0, 0), b2, voffB); PG8_STAGE(PG8_SB(0, 1), b2 + hstepB, voffB); PG8_STAGE(PG8_SA(0, 0), a2, voffA);
;             PG8_WAIT_V(8); PG8_WAIT_L(0); PG8_BAR; PG8_MMA(1, 0, At, B0); PG8_MMA(1, 1, At, B1); PG8_BAR; PG8_SCHED;
.LBB0_770:
	s_add_u32 s3, s10, 0xfffc0080
	s_addc_u32 s42, s11, -1
	s_add_i32 s71, 0, 0x10000
	s_cmp_eq_u32 s70, 12
	s_cselect_b32 s45, s60, s42
	s_cselect_b32 s44, s61, s3
	s_cselect_b32 s43, s62, s65
	s_cselect_b32 s42, s63, s64
	s_add_i32 s3, 0, 0x14000
	v_add_u32_e32 v142, s71, v183
	v_add_u32_e32 v158, s3, v183
	ds_read_b128 v[130:133], v142
	ds_read_b128 v[134:137], v142 offset:1024
	ds_read_b128 v[138:141], v142 offset:2048
	ds_read_b128 v[142:145], v142 offset:3072
	ds_read_b128 v[146:149], v158
	ds_read_b128 v[150:153], v158 offset:1024
	ds_read_b128 v[154:157], v158 offset:2048
	ds_read_b128 v[158:161], v158 offset:3072
	s_add_i32 m0, s9, 0xc000
	ds_read_b128 v[174:177], v194
	ds_read_b128 v[196:199], v194 offset:1024
	ds_read_b128 v[200:203], v194 offset:2048
	ds_read_b128 v[204:207], v194 offset:3072
	ds_read_b128 v[208:211], v194 offset:4096
	ds_read_b128 v[212:215], v194 offset:5120
	ds_read_b128 v[216:219], v194 offset:6144
	ds_read_b128 v[220:223], v194 offset:7168
	global_load_lds_dwordx4 v172, s[10:11]
	s_add_i32 m0, s9, 0xe000
	s_nop 0
	global_load_lds_dwordx4 v170, s[10:11]
	s_waitcnt vmcnt(8)
	s_waitcnt lgkmcnt(0)
	s_barrier
	s_setprio 1
	s_waitcnt lgkmcnt(0)
	v_mfma_f32_16x16x32_bf16 v[126:129], v[130:133], v[174:177], v[126:129]
	v_mfma_f32_16x16x32_bf16 v[118:121], v[138:141], v[174:177], v[118:121]
	v_mfma_f32_16x16x32_bf16 v[110:113], v[130:133], v[200:203], v[110:113]
	v_mfma_f32_16x16x32_bf16 v[102:105], v[138:141], v[200:203], v[102:105]
	v_mfma_f32_16x16x32_bf16 v[94:97], v[130:133], v[208:211], v[94:97]
	v_mfma_f32_16x16x32_bf16 v[86:89], v[138:141], v[208:211], v[86:89]
	v_mfma_f32_16x16x32_bf16 v[78:81], v[130:133], v[216:219], v[78:81]
	v_mfma_f32_16x16x32_bf16 v[70:73], v[138:141], v[216:219], v[70:73]
	v_mfma_f32_16x16x32_bf16 v[126:129], v[134:137], v[196:199], v[126:129]
	v_mfma_f32_16x16x32_bf16 v[118:121], v[142:145], v[196:199], v[118:121]
	v_mfma_f32_16x16x32_bf16 v[110:113], v[134:137], v[204:207], v[110:113]
	v_mfma_f32_16x16x32_bf16 v[102:105], v[142:145], v[204:207], v[102:105]
	v_mfma_f32_16x16x32_bf16 v[94:97], v[134:137], v[212:215], v[94:97]
	v_mfma_f32_16x16x32_bf16 v[86:89], v[142:145], v[212:215], v[86:89]
	v_mfma_f32_16x16x32_bf16 v[78:81], v[134:137], v[220:223], v[78:81]
	v_mfma_f32_16x16x32_bf16 v[70:73], v[142:145], v[220:223], v[70:73]
	s_setprio 0
	s_setprio 1
	v_mfma_f32_16x16x32_bf16 v[122:125], v[146:149], v[174:177], v[122:125]
	v_mfma_f32_16x16x32_bf16 v[114:117], v[154:157], v[174:177], v[114:117]
	v_mfma_f32_16x16x32_bf16 v[106:109], v[146:149], v[200:203], v[106:109]
	v_mfma_f32_16x16x32_bf16 v[98:101], v[154:157], v[200:203], v[98:101]
	v_mfma_f32_16x16x32_bf16 v[90:93], v[146:149], v[208:211], v[90:93]
	v_mfma_f32_16x16x32_bf16 v[82:85], v[154:157], v[208:211], v[82:85]
	v_mfma_f32_16x16x32_bf16 v[74:77], v[146:149], v[216:219], v[74:77]
	v_mfma_f32_16x16x32_bf16 v[66:69], v[154:157], v[216:219], v[66:69]
	v_mfma_f32_16x16x32_bf16 v[122:125], v[150:153], v[196:199], v[122:125]
	v_mfma_f32_16x16x32_bf16 v[114:117], v[158:161], v[196:199], v[114:117]
	v_mfma_f32_16x16x32_bf16 v[106:109], v[150:153], v[204:207], v[106:109]
	v_mfma_f32_16x16x32_bf16 v[98:101], v[158:161], v[204:207], v[98:101]
	s_setprio 2
	s_barrier
	v_mfma_f32_16x16x32_bf16 v[90:93], v[150:153], v[212:215], v[90:93]
	v_mfma_f32_16x16x32_bf16 v[82:85], v[158:161], v[212:215], v[82:85]
	v_mfma_f32_16x16x32_bf16 v[74:77], v[150:153], v[220:223], v[74:77]
	v_mfma_f32_16x16x32_bf16 v[66:69], v[158:161], v[220:223], v[66:69]
	s_setprio 0
	s_add_i32 s71, s71, s7
	s_mov_b32 m0, s71
	ds_read_b128 v[174:177], v194 offset:16384
	ds_read_b128 v[196:199], v194 offset:17408
	ds_read_b128 v[200:203], v194 offset:18432
	ds_read_b128 v[204:207], v194 offset:19456
	ds_read_b128 v[208:211], v194 offset:20480
	ds_read_b128 v[212:215], v194 offset:21504
	ds_read_b128 v[216:219], v194 offset:22528
	ds_read_b128 v[220:223], v194 offset:23552
	global_load_lds_dwordx4 v0, s[42:43]
	s_add_i32 m0, s71, 0x2000
	s_add_u32 s96, s42, 0x40000
	s_addc_u32 s97, s43, 0
	s_add_i32 s3, s3, s7
	global_load_lds_dwordx4 v164, s[42:43]
	s_mov_b32 m0, s3
	s_nop 0
	global_load_lds_dwordx4 v0, s[96:97]
	s_add_i32 m0, s3, 0x2000
	s_nop 0
	global_load_lds_dwordx4 v164, s[96:97]
	s_mov_b32 m0, s9
	s_nop 0
	global_load_lds_dwordx4 v168, s[44:45]
	s_mov_b32 m0, s56
	s_nop 0
	global_load_lds_dwordx4 v166, s[44:45]
	s_waitcnt vmcnt(8)
	s_waitcnt lgkmcnt(0)
	s_barrier
	s_setprio 1
	s_waitcnt lgkmcnt(0)
	v_mfma_f32_16x16x32_bf16 v[62:65], v[130:133], v[174:177], v[62:65]
	v_mfma_f32_16x16x32_bf16 v[54:57], v[138:141], v[174:177], v[54:57]
	v_mfma_f32_16x16x32_bf16 v[46:49], v[130:133], v[200:203], v[46:49]
	v_mfma_f32_16x16x32_bf16 v[38:41], v[138:141], v[200:203], v[38:41]
	v_mfma_f32_16x16x32_bf16 v[30:33], v[130:133], v[208:211], v[30:33]
	v_mfma_f32_16x16x32_bf16 v[22:25], v[138:141], v[208:211], v[22:25]
	v_mfma_f32_16x16x32_bf16 v[14:17], v[130:133], v[216:219], v[14:17]
	v_mfma_f32_16x16x32_bf16 v[6:9], v[138:141], v[216:219], v[6:9]
	v_mfma_f32_16x16x32_bf16 v[62:65], v[134:137], v[196:199], v[62:65]
	v_mfma_f32_16x16x32_bf16 v[54:57], v[142:145], v[196:199], v[54:57]
	v_mfma_f32_16x16x32_bf16 v[46:49], v[134:137], v[204:207], v[46:49]
	v_mfma_f32_16x16x32_bf16 v[38:41], v[142:145], v[204:207], v[38:41]
	v_mfma_f32_16x16x32_bf16 v[30:33], v[134:137], v[212:215], v[30:33]
	v_mfma_f32_16x16x32_bf16 v[22:25], v[142:145], v[212:215], v[22:25]
	v_mfma_f32_16x16x32_bf16 v[14:17], v[134:137], v[220:223], v[14:17]
	v_mfma_f32_16x16x32_bf16 v[6:9], v[142:145], v[220:223], v[6:9]
	s_setprio 0
	s_setprio 1
	v_mfma_f32_16x16x32_bf16 v[58:61], v[146:149], v[174:177], v[58:61]
	v_mfma_f32_16x16x32_bf16 v[50:53], v[154:157], v[174:177], v[50:53]
	v_mfma_f32_16x16x32_bf16 v[42:45], v[146:149], v[200:203], v[42:45]
	v_mfma_f32_16x16x32_bf16 v[34:37], v[154:157], v[200:203], v[34:37]
	v_mfma_f32_16x16x32_bf16 v[26:29], v[146:149], v[208:211], v[26:29]
	v_mfma_f32_16x16x32_bf16 v[18:21], v[154:157], v[208:211], v[18:21]
	v_mfma_f32_16x16x32_bf16 v[10:13], v[146:149], v[216:219], v[10:13]
	v_mfma_f32_16x16x32_bf16 v[2:5], v[154:157], v[216:219], v[2:5]
	v_mfma_f32_16x16x32_bf16 v[58:61], v[150:153], v[196:199], v[58:61]
	v_mfma_f32_16x16x32_bf16 v[50:53], v[158:161], v[196:199], v[50:53]
	v_mfma_f32_16x16x32_bf16 v[42:45], v[150:153], v[204:207], v[42:45]
	v_mfma_f32_16x16x32_bf16 v[34:37], v[158:161], v[204:207], v[34:37]
	s_setprio 2
	s_barrier
; #define PG8_STAGE(bufoff, gbase, voff) do { _Pragma("unroll") for (int _i = 0; _i < 2; ++_i) \
;         __builtin_amdgcn_global_load_lds((const unsigned*)((const char*)(gbase) + (voff)[_i]), (LAS unsigned*)(lds + (bufoff) + ldsw + _i * 8192), 16, 0, 0); } while (0)
; #define PG8_LDA(dst, b, h) do { _Pragma("unroll") for (int m = 0; m < 4; ++m) _Pragma("unroll") for (int k = 0; k < 2; ++k) dst[m][k] = *(const LAS bf16x8*)(lds + PG8_SA(b, h) + aoff + m * 2048 + k * 1024); } while (0)
; #define PG8_LDB(dst, b, h) do { _Pragma("unroll") for (int n = 0; n < 2; ++n) _Pragma("unroll") for (int k = 0; k < 2; ++k) dst[n][k] = *(const LAS bf16x8*)(lds + PG8_SB(b, h) + boff + n * 2048 + k * 1024); } while (0)
; #define PG8_MMA(ai, bj, At, Bt) do { __builtin_amdgcn_s_setprio(1); _Pragma("unroll") for (int m = 0; m < 4; ++m) _Pragma("unroll") for (int n = 0; n < 2; ++n) _Pragma("unroll") for (int k = 0; k < 2; ++k) \
;         acc[ai][bj][m][n] = __builtin_amdgcn_mfma_f32_16x16x32_bf16(Bt[n][k], At[m][k], acc[ai][bj][m][n], 0, 0, 0); __builtin_amdgcn_s_setprio(0); } while (0)
; #define PG8_WAIT_V(n) asm volatile("s_waitcnt vmcnt(" #n ")" ::: "memory")
; #define PG8_WAIT_L(n) asm volatile("s_waitcnt lgkmcnt(" #n ")" ::: "memory")
; #define PG8_BAR __builtin_amdgcn_s_barrier()
; #define PG8_SCHED __builtin_amdgcn_sched_barrier(0)
; template <class Epi, class Sched>
; __device__ __forceinline__ void gemm_phase(LAS unsigned char* lds, const Gemm g, Sched S, const Epi& E) {
;     ...
;             PG8_WAIT_V(8); PG8_WAIT_L(0); PG8_BAR; PG8_MMA(1, 0, At, B0); PG8_MMA(1, 1, At, B1); PG8_BAR; PG8_SCHED;
;             PG8_LDB(B0, 1, 0); PG8_LDB(B1, 1, 1); PG8_SCHED; PG8_LDA(At, 1, 0); PG8_STAGE(PG8_SA(0, 1), a2 + hstepA, voffA);
;             PG8_WAIT_V(8); PG8_WAIT_L(0); PG8_BAR; PG8_MMA(0, 0, At, B0); PG8_MMA(0, 1, At, B1); PG8_BAR; PG8_SCHED;
	v_mfma_f32_16x16x32_bf16 v[26:29], v[150:153], v[212:215], v[26:29]
	v_mfma_f32_16x16x32_bf16 v[18:21], v[158:161], v[212:215], v[18:21]
	v_mfma_f32_16x16x32_bf16 v[10:13], v[150:153], v[220:223], v[10:13]
	v_mfma_f32_16x16x32_bf16 v[2:5], v[158:161], v[220:223], v[2:5]
	s_setprio 0
	s_add_i32 s3, 0, 0x18000
	s_add_i32 s71, 0, 0x1c000
	v_add_u32_e32 v142, s3, v183
	v_add_u32_e32 v158, s71, v183
	ds_read_b128 v[130:133], v142
	ds_read_b128 v[134:137], v142 offset:1024
	ds_read_b128 v[138:141], v142 offset:2048
	ds_read_b128 v[142:145], v142 offset:3072
	ds_read_b128 v[146:149], v158
	ds_read_b128 v[150:153], v158 offset:1024
	ds_read_b128 v[154:157], v158 offset:2048
	ds_read_b128 v[158:161], v158 offset:3072
	s_add_u32 s44, s44, 0x40000
	s_addc_u32 s45, s45, 0
	s_mov_b32 m0, s67
	ds_read_b128 v[174:177], v194 offset:32768
	ds_read_b128 v[196:199], v194 offset:33792
	ds_read_b128 v[200:203], v194 offset:34816
	ds_read_b128 v[204:207], v194 offset:35840
	ds_read_b128 v[208:211], v194 offset:36864
	ds_read_b128 v[212:215], v194 offset:37888
	ds_read_b128 v[216:219], v194 offset:38912
	ds_read_b128 v[220:223], v194 offset:39936
	global_load_lds_dwordx4 v168, s[44:45]
	s_mov_b32 m0, s72
	s_nop 0
	global_load_lds_dwordx4 v166, s[44:45]
	s_waitcnt vmcnt(8)
	s_waitcnt lgkmcnt(0)
	s_barrier
	s_setprio 1
	s_waitcnt lgkmcnt(0)
	v_mfma_f32_16x16x32_bf16 v[126:129], v[130:133], v[174:177], v[126:129]
	v_mfma_f32_16x16x32_bf16 v[118:121], v[138:141], v[174:177], v[118:121]
	v_mfma_f32_16x16x32_bf16 v[110:113], v[130:133], v[200:203], v[110:113]
	v_mfma_f32_16x16x32_bf16 v[102:105], v[138:141], v[200:203], v[102:105]
	v_mfma_f32_16x16x32_bf16 v[94:97], v[130:133], v[208:211], v[94:97]
	v_mfma_f32_16x16x32_bf16 v[86:89], v[138:141], v[208:211], v[86:89]
	v_mfma_f32_16x16x32_bf16 v[78:81], v[130:133], v[216:219], v[78:81]
	v_mfma_f32_16x16x32_bf16 v[70:73], v[138:141], v[216:219], v[70:73]
	v_mfma_f32_16x16x32_bf16 v[126:129], v[134:137], v[196:199], v[126:129]
	v_mfma_f32_16x16x32_bf16 v[118:121], v[142:145], v[196:199], v[118:121]
	v_mfma_f32_16x16x32_bf16 v[110:113], v[134:137], v[204:207], v[110:113]
	v_mfma_f32_16x16x32_bf16 v[102:105], v[142:145], v[204:207], v[102:105]
	v_mfma_f32_16x16x32_bf16 v[94:97], v[134:137], v[212:215], v[94:97]
	v_mfma_f32_16x16x32_bf16 v[86:89], v[142:145], v[212:215], v[86:89]
	v_mfma_f32_16x16x32_bf16 v[78:81], v[134:137], v[220:223], v[78:81]
	v_mfma_f32_16x16x32_bf16 v[70:73], v[142:145], v[220:223], v[70:73]
	s_setprio 0
	s_setprio 1
	v_mfma_f32_16x16x32_bf16 v[122:125], v[146:149], v[174:177], v[122:125]
	v_mfma_f32_16x16x32_bf16 v[114:117], v[154:157], v[174:177], v[114:117]
	v_mfma_f32_16x16x32_bf16 v[106:109], v[146:149], v[200:203], v[106:109]
	v_mfma_f32_16x16x32_bf16 v[98:101], v[154:157], v[200:203], v[98:101]
	v_mfma_f32_16x16x32_bf16 v[90:93], v[146:149], v[208:211], v[90:93]
	v_mfma_f32_16x16x32_bf16 v[82:85], v[154:157], v[208:211], v[82:85]
	v_mfma_f32_16x16x32_bf16 v[74:77], v[146:149], v[216:219], v[74:77]
	v_mfma_f32_16x16x32_bf16 v[66:69], v[154:157], v[216:219], v[66:69]
	v_mfma_f32_16x16x32_bf16 v[122:125], v[150:153], v[196:199], v[122:125]
	v_mfma_f32_16x16x32_bf16 v[114:117], v[158:161], v[196:199], v[114:117]
	v_mfma_f32_16x16x32_bf16 v[106:109], v[150:153], v[204:207], v[106:109]
	v_mfma_f32_16x16x32_bf16 v[98:101], v[158:161], v[204:207], v[98:101]
	s_setprio 2
	s_barrier
; #define PG8_STAGE(bufoff, gbase, voff) do { _Pragma("unroll") for (int _i = 0; _i < 2; ++_i) \
;         __builtin_amdgcn_global_load_lds((const unsigned*)((const char*)(gbase) + (voff)[_i]), (LAS unsigned*)(lds + (bufoff) + ldsw + _i * 8192), 16, 0, 0); } while (0)
; #define PG8_LDA(dst, b, h) do { _Pragma("unroll") for (int m = 0; m < 4; ++m) _Pragma("unroll") for (int k = 0; k < 2; ++k) dst[m][k] = *(const LAS bf16x8*)(lds + PG8_SA(b, h) + aoff + m * 2048 + k * 1024); } while (0)
; #define PG8_MMA(ai, bj, At, Bt) do { __builtin_amdgcn_s_setprio(1); _Pragma("unroll") for (int m = 0; m < 4; ++m) _Pragma("unroll") for (int n = 0; n < 2; ++n) _Pragma("unroll") for (int k = 0; k < 2; ++k) \
;         acc[ai][bj][m][n] = __builtin_amdgcn_mfma_f32_16x16x32_bf16(Bt[n][k], At[m][k], acc[ai][bj][m][n], 0, 0, 0); __builtin_amdgcn_s_setprio(0); } while (0)
; #define PG8_WAIT_V(n) asm volatile("s_waitcnt vmcnt(" #n ")" ::: "memory")
; #define PG8_WAIT_L(n) asm volatile("s_waitcnt lgkmcnt(" #n ")" ::: "memory")
; #define PG8_BAR __builtin_amdgcn_s_barrier()
; #define PG8_SCHED __builtin_amdgcn_sched_barrier(0)
; template <class Epi, class Sched>
; __device__ __forceinline__ void gemm_phase(LAS unsigned char* lds, const Gemm g, Sched S, const Epi& E) {
;     ...
;             PG8_WAIT_V(8); PG8_WAIT_L(0); PG8_BAR; PG8_MMA(0, 0, At, B0); PG8_MMA(0, 1, At, B1); PG8_BAR; PG8_SCHED;
;             PG8_LDA(At, 1, 1); PG8_STAGE(PG8_SB(1, 0), b3, voffB); PG8_STAGE(PG8_SB(1, 1), b3 + hstepB, voffB); PG8_STAGE(PG8_SA(1, 0), a3, voffA);
;             PG8_WAIT_V(8); PG8_WAIT_L(0); PG8_BAR; PG8_MMA(1, 0, At, B0); PG8_MMA(1, 1, At, B1); PG8_BAR; PG8_SCHED;
;         }
;         if (wr == 0) PG8_BAR;
	v_mfma_f32_16x16x32_bf16 v[90:93], v[150:153], v[212:215], v[90:93]
	v_mfma_f32_16x16x32_bf16 v[82:85], v[158:161], v[212:215], v[82:85]
	v_mfma_f32_16x16x32_bf16 v[74:77], v[150:153], v[220:223], v[74:77]
	v_mfma_f32_16x16x32_bf16 v[66:69], v[158:161], v[220:223], v[66:69]
	s_setprio 0
	s_add_i32 s3, s3, s7
	s_add_u32 s100, s42, 0x80
	s_addc_u32 s101, s43, 0
	s_mov_b32 m0, s3
	ds_read_b128 v[174:177], v194 offset:49152
	ds_read_b128 v[196:199], v194 offset:50176
	ds_read_b128 v[200:203], v194 offset:51200
	ds_read_b128 v[204:207], v194 offset:52224
	ds_read_b128 v[208:211], v194 offset:53248
	ds_read_b128 v[212:215], v194 offset:54272
	ds_read_b128 v[216:219], v194 offset:55296
	ds_read_b128 v[220:223], v194 offset:56320
	global_load_lds_dwordx4 v0, s[100:101]
	s_add_i32 m0, s3, 0x2000
	s_add_u32 s42, s42, 0x40080
	s_addc_u32 s43, s43, 0
	s_add_u32 s96, s44, 0xfffc0080
	s_addc_u32 s97, s45, -1
	s_add_i32 s3, s71, s7
	global_load_lds_dwordx4 v164, s[100:101]
	s_mov_b32 m0, s3
	s_nop 0
	global_load_lds_dwordx4 v0, s[42:43]
	s_add_i32 m0, s3, 0x2000
	s_nop 0
	global_load_lds_dwordx4 v164, s[42:43]
	s_mov_b32 m0, s73
	s_nop 0
	global_load_lds_dwordx4 v168, s[96:97]
	s_mov_b32 m0, s76
	s_nop 0
	global_load_lds_dwordx4 v166, s[96:97]
	s_waitcnt vmcnt(8)
	s_waitcnt lgkmcnt(0)
	s_barrier
	s_setprio 1
	s_waitcnt lgkmcnt(0)
	v_mfma_f32_16x16x32_bf16 v[62:65], v[130:133], v[174:177], v[62:65]
	v_mfma_f32_16x16x32_bf16 v[54:57], v[138:141], v[174:177], v[54:57]
	v_mfma_f32_16x16x32_bf16 v[46:49], v[130:133], v[200:203], v[46:49]
	v_mfma_f32_16x16x32_bf16 v[38:41], v[138:141], v[200:203], v[38:41]
	v_mfma_f32_16x16x32_bf16 v[30:33], v[130:133], v[208:211], v[30:33]
	v_mfma_f32_16x16x32_bf16 v[22:25], v[138:141], v[208:211], v[22:25]
	v_mfma_f32_16x16x32_bf16 v[14:17], v[130:133], v[216:219], v[14:17]
	v_mfma_f32_16x16x32_bf16 v[6:9], v[138:141], v[216:219], v[6:9]
	v_mfma_f32_16x16x32_bf16 v[62:65], v[134:137], v[196:199], v[62:65]
	v_mfma_f32_16x16x32_bf16 v[54:57], v[142:145], v[196:199], v[54:57]
	v_mfma_f32_16x16x32_bf16 v[46:49], v[134:137], v[204:207], v[46:49]
	v_mfma_f32_16x16x32_bf16 v[38:41], v[142:145], v[204:207], v[38:41]
	v_mfma_f32_16x16x32_bf16 v[30:33], v[134:137], v[212:215], v[30:33]
	v_mfma_f32_16x16x32_bf16 v[22:25], v[142:145], v[212:215], v[22:25]
	v_mfma_f32_16x16x32_bf16 v[14:17], v[134:137], v[220:223], v[14:17]
	v_mfma_f32_16x16x32_bf16 v[6:9], v[142:145], v[220:223], v[6:9]
	s_setprio 0
	s_setprio 1
	v_mfma_f32_16x16x32_bf16 v[58:61], v[146:149], v[174:177], v[58:61]
	v_mfma_f32_16x16x32_bf16 v[50:53], v[154:157], v[174:177], v[50:53]
	v_mfma_f32_16x16x32_bf16 v[42:45], v[146:149], v[200:203], v[42:45]
	v_mfma_f32_16x16x32_bf16 v[34:37], v[154:157], v[200:203], v[34:37]
	v_mfma_f32_16x16x32_bf16 v[26:29], v[146:149], v[208:211], v[26:29]
	v_mfma_f32_16x16x32_bf16 v[18:21], v[154:157], v[208:211], v[18:21]
	v_mfma_f32_16x16x32_bf16 v[10:13], v[146:149], v[216:219], v[10:13]
	v_mfma_f32_16x16x32_bf16 v[2:5], v[154:157], v[216:219], v[2:5]
	v_mfma_f32_16x16x32_bf16 v[58:61], v[150:153], v[196:199], v[58:61]
	v_mfma_f32_16x16x32_bf16 v[50:53], v[158:161], v[196:199], v[50:53]
	v_mfma_f32_16x16x32_bf16 v[42:45], v[150:153], v[204:207], v[42:45]
	v_mfma_f32_16x16x32_bf16 v[34:37], v[158:161], v[204:207], v[34:37]
	s_setprio 2
	s_barrier
	v_mfma_f32_16x16x32_bf16 v[26:29], v[150:153], v[212:215], v[26:29]
	v_mfma_f32_16x16x32_bf16 v[18:21], v[158:161], v[212:215], v[18:21]
	v_mfma_f32_16x16x32_bf16 v[10:13], v[150:153], v[220:223], v[10:13]
	v_mfma_f32_16x16x32_bf16 v[2:5], v[158:161], v[220:223], v[2:5]
	s_setprio 0
	s_add_i32 s70, s70, 2
	s_add_u32 s64, s64, 0x100
	s_addc_u32 s65, s65, 0
	s_add_u32 s10, s10, 0x100
	s_addc_u32 s11, s11, 0
	s_cmp_gt_u32 s70, 13
	s_cbranch_scc0 .LBB0_770
	s_and_b64 vcc, exec, s[30:31]
	s_cbranch_vccz .LBB0_773
	s_barrier
